# attention O epilogue rewritten: DPP pair pack + per-wave LDS transpose + 8 dwordx4 row stores instead of 64 masked dword stores with bpermute; on top of v6
# speedup vs baseline: 1.0043x; 1.0043x over previous
; #define SBAR() __builtin_amdgcn_sched_barrier(0)
; __device__ __forceinline__ int crow(int r, int hi) { return (r & 3) + 8 * (r >> 2) + 4 * hi; }
; #define SEAM_K0() do { VMWN(NQL); if constexpr (F32) { SWRITE_KF(0); SBAR(); SLOAD_F((const float*)(nxt.K + 1024), kbn); } else { SWRITE_HK(0); } SBAR(); } while (0)
; template <class TIn, class TOut>
; __device__ __forceinline__ void causal_swa_block(const BlockRef<TIn, TOut>& cur, const BlockRef<TIn, TOut>& nxt, int skv, int W, char* lds, Seam<TIn>& S, const float* csl) {
;     ...
;     SBAR(); SEAM_K0();
;     if (hi == 0) li_l[r32] = l_reg; asm volatile("s_waitcnt lgkmcnt(0)" ::: "memory");
;     float rli[16];
; #pragma unroll
;     for (int r = 0; r < 16; ++r) rli[r] = __builtin_amdgcn_rcpf(li_l[crow(r, hi)]);
;     TOut* Ow = cur.O + (size_t)(wid * QBLK) * OP;
; #pragma unroll
;     for (int r = 0; r < 16; ++r) { const int orow = crow(r, hi);
; #pragma unroll
;         for (int d0 = 0; d0 < 4; ++d0) { const float v = o[d0][r] * rli[r];
;             if constexpr (same_t<TOut, float>::v) { Ow[(size_t)orow * OP + d0 * 32 + r32] = v; }
;             else { const float vn = __shfl_xor(v, 1);
;                    if ((r32 & 1) == 0) *(unsigned*)(Ow + (size_t)orow * OP + d0 * 32 + r32) = cvtpk(v, vn); } } }
.LBB0_385:
	s_waitcnt vmcnt(8)
	s_waitcnt vmcnt(1)
	ds_write_b128 v212, v[100:103] offset:32768
	s_waitcnt vmcnt(0)
	ds_write_b128 v212, v[104:107] offset:40960
	v_cmp_gt_u32_e32 vcc, 32, v213
	s_and_saveexec_b64 s[14:15], vcc
	ds_write_b32 v215, v98
	s_or_b64 exec, exec, s[14:15]
	s_waitcnt lgkmcnt(0)
	ds_read_b128 v[76:79], v214
	ds_read_b128 v[72:75], v214 offset:32
	ds_read_b128 v[68:71], v214 offset:64
	ds_read_b128 v[64:67], v214 offset:96
	s_lshl_b32 s14, s58, 1
	v_readlane_b32 s15, v254, 30
	s_nop 0
	s_add_u32 s14, s15, s14
	v_readlane_b32 s15, v254, 31
	s_nop 0
	s_addc_u32 s15, s15, 0
	s_lshl_b32 s16, s49, 11
	s_add_u32 s16, s14, s16
	s_addc_u32 s17, s15, 0
	s_ashr_i32 s49, s48, 31
	s_lshl_b64 s[14:15], s[48:49], 11
	s_add_u32 s14, s16, s14
	s_addc_u32 s15, s17, s15
	s_lshl_b32 s16, s48, 8
	s_add_i32 s16, s16, 0x10800
	v_lshlrev_b32_e32 v80, 10, v210
	v_lshl_add_u32 v80, v211, 1, v80
	v_and_b32_e32 v81, 63, v209
	v_add_u32_e32 v82, s16, v80
	v_lshlrev_b32_e32 v83, 4, v81
	v_add_u32_e32 v83, s16, v83
	v_and_b32_e32 v80, 1, v209
	v_cmp_eq_u32_e64 s[40:41], 0, v80
	s_waitcnt lgkmcnt(0)
	v_rcp_f32_e32 v76, v76
	v_rcp_f32_e32 v77, v77
	v_rcp_f32_e32 v78, v78
	v_rcp_f32_e32 v79, v79
	v_rcp_f32_e32 v72, v72
	v_rcp_f32_e32 v73, v73
	v_rcp_f32_e32 v74, v74
	v_rcp_f32_e32 v75, v75
	v_rcp_f32_e32 v68, v68
	v_rcp_f32_e32 v69, v69
	v_rcp_f32_e32 v70, v70
	v_rcp_f32_e32 v71, v71
	v_rcp_f32_e32 v64, v64
	v_rcp_f32_e32 v65, v65
	v_rcp_f32_e32 v66, v66
	v_rcp_f32_e32 v67, v67
	s_nop 0
	v_mul_f32_e32 v48, v48, v76
	v_mul_f32_e32 v32, v32, v76
	v_mul_f32_e32 v16, v16, v76
	v_mul_f32_e32 v0, v0, v76
	v_mov_b32_dpp v80, v48 quad_perm:[1,0,3,2] row_mask:0xf bank_mask:0xf
	v_mov_b32_dpp v81, v32 quad_perm:[1,0,3,2] row_mask:0xf bank_mask:0xf
	v_cvt_pk_bf16_f32 v48, v48, v80
	v_cvt_pk_bf16_f32 v32, v32, v81
	v_mov_b32_dpp v80, v16 quad_perm:[1,0,3,2] row_mask:0xf bank_mask:0xf
	v_mov_b32_dpp v81, v0 quad_perm:[1,0,3,2] row_mask:0xf bank_mask:0xf
	v_cvt_pk_bf16_f32 v16, v16, v80
	v_cvt_pk_bf16_f32 v0, v0, v81
	v_mul_f32_e32 v49, v49, v77
	v_mul_f32_e32 v33, v33, v77
	v_mul_f32_e32 v17, v17, v77
	v_mul_f32_e32 v1, v1, v77
	v_mov_b32_dpp v80, v49 quad_perm:[1,0,3,2] row_mask:0xf bank_mask:0xf
	v_mov_b32_dpp v81, v33 quad_perm:[1,0,3,2] row_mask:0xf bank_mask:0xf
	v_cvt_pk_bf16_f32 v49, v49, v80
	v_cvt_pk_bf16_f32 v33, v33, v81
	v_mov_b32_dpp v80, v17 quad_perm:[1,0,3,2] row_mask:0xf bank_mask:0xf
	v_mov_b32_dpp v81, v1 quad_perm:[1,0,3,2] row_mask:0xf bank_mask:0xf
	v_cvt_pk_bf16_f32 v17, v17, v80
	v_cvt_pk_bf16_f32 v1, v1, v81
	v_mul_f32_e32 v50, v50, v78
	v_mul_f32_e32 v34, v34, v78
	v_mul_f32_e32 v18, v18, v78
	v_mul_f32_e32 v2, v2, v78
	v_mov_b32_dpp v80, v50 quad_perm:[1,0,3,2] row_mask:0xf bank_mask:0xf
	v_mov_b32_dpp v81, v34 quad_perm:[1,0,3,2] row_mask:0xf bank_mask:0xf
	v_cvt_pk_bf16_f32 v50, v50, v80
	v_cvt_pk_bf16_f32 v34, v34, v81
	v_mov_b32_dpp v80, v18 quad_perm:[1,0,3,2] row_mask:0xf bank_mask:0xf
	v_mov_b32_dpp v81, v2 quad_perm:[1,0,3,2] row_mask:0xf bank_mask:0xf
	v_cvt_pk_bf16_f32 v18, v18, v80
	v_cvt_pk_bf16_f32 v2, v2, v81
	v_mul_f32_e32 v51, v51, v79
	v_mul_f32_e32 v35, v35, v79
	v_mul_f32_e32 v19, v19, v79
	v_mul_f32_e32 v3, v3, v79
	v_mov_b32_dpp v80, v51 quad_perm:[1,0,3,2] row_mask:0xf bank_mask:0xf
	v_mov_b32_dpp v81, v35 quad_perm:[1,0,3,2] row_mask:0xf bank_mask:0xf
	v_cvt_pk_bf16_f32 v51, v51, v80
	v_cvt_pk_bf16_f32 v35, v35, v81
	v_mov_b32_dpp v80, v19 quad_perm:[1,0,3,2] row_mask:0xf bank_mask:0xf
	v_mov_b32_dpp v81, v3 quad_perm:[1,0,3,2] row_mask:0xf bank_mask:0xf
	v_cvt_pk_bf16_f32 v19, v19, v80
	v_cvt_pk_bf16_f32 v3, v3, v81
	v_mul_f32_e32 v52, v52, v72
	v_mul_f32_e32 v36, v36, v72
	v_mul_f32_e32 v20, v20, v72
	v_mul_f32_e32 v4, v4, v72
	v_mov_b32_dpp v80, v52 quad_perm:[1,0,3,2] row_mask:0xf bank_mask:0xf
	v_mov_b32_dpp v81, v36 quad_perm:[1,0,3,2] row_mask:0xf bank_mask:0xf
	v_cvt_pk_bf16_f32 v52, v52, v80
	v_cvt_pk_bf16_f32 v36, v36, v81
	v_mov_b32_dpp v80, v20 quad_perm:[1,0,3,2] row_mask:0xf bank_mask:0xf
	v_mov_b32_dpp v81, v4 quad_perm:[1,0,3,2] row_mask:0xf bank_mask:0xf
	v_cvt_pk_bf16_f32 v20, v20, v80
	v_cvt_pk_bf16_f32 v4, v4, v81
	v_mul_f32_e32 v53, v53, v73
	v_mul_f32_e32 v37, v37, v73
	v_mul_f32_e32 v21, v21, v73
	v_mul_f32_e32 v5, v5, v73
	v_mov_b32_dpp v80, v53 quad_perm:[1,0,3,2] row_mask:0xf bank_mask:0xf
	v_mov_b32_dpp v81, v37 quad_perm:[1,0,3,2] row_mask:0xf bank_mask:0xf
	v_cvt_pk_bf16_f32 v53, v53, v80
	v_cvt_pk_bf16_f32 v37, v37, v81
	v_mov_b32_dpp v80, v21 quad_perm:[1,0,3,2] row_mask:0xf bank_mask:0xf
	v_mov_b32_dpp v81, v5 quad_perm:[1,0,3,2] row_mask:0xf bank_mask:0xf
	v_cvt_pk_bf16_f32 v21, v21, v80
	v_cvt_pk_bf16_f32 v5, v5, v81
	v_mul_f32_e32 v54, v54, v74
	v_mul_f32_e32 v38, v38, v74
	v_mul_f32_e32 v22, v22, v74
	v_mul_f32_e32 v6, v6, v74
	v_mov_b32_dpp v80, v54 quad_perm:[1,0,3,2] row_mask:0xf bank_mask:0xf
	v_mov_b32_dpp v81, v38 quad_perm:[1,0,3,2] row_mask:0xf bank_mask:0xf
	v_cvt_pk_bf16_f32 v54, v54, v80
	v_cvt_pk_bf16_f32 v38, v38, v81
	v_mov_b32_dpp v80, v22 quad_perm:[1,0,3,2] row_mask:0xf bank_mask:0xf
	v_mov_b32_dpp v81, v6 quad_perm:[1,0,3,2] row_mask:0xf bank_mask:0xf
	v_cvt_pk_bf16_f32 v22, v22, v80
	v_cvt_pk_bf16_f32 v6, v6, v81
	v_mul_f32_e32 v55, v55, v75
	v_mul_f32_e32 v39, v39, v75
	v_mul_f32_e32 v23, v23, v75
	v_mul_f32_e32 v7, v7, v75
	v_mov_b32_dpp v80, v55 quad_perm:[1,0,3,2] row_mask:0xf bank_mask:0xf
	v_mov_b32_dpp v81, v39 quad_perm:[1,0,3,2] row_mask:0xf bank_mask:0xf
	v_cvt_pk_bf16_f32 v55, v55, v80
	v_cvt_pk_bf16_f32 v39, v39, v81
	v_mov_b32_dpp v80, v23 quad_perm:[1,0,3,2] row_mask:0xf bank_mask:0xf
	v_mov_b32_dpp v81, v7 quad_perm:[1,0,3,2] row_mask:0xf bank_mask:0xf
; __device__ __forceinline__ int crow(int r, int hi) { return (r & 3) + 8 * (r >> 2) + 4 * hi; }
; template <class TIn, class TOut>
; __device__ __forceinline__ void causal_swa_block(const BlockRef<TIn, TOut>& cur, const BlockRef<TIn, TOut>& nxt, int skv, int W, char* lds, Seam<TIn>& S, const float* csl) {
;     ...
;     for (int r = 0; r < 16; ++r) { const int orow = crow(r, hi);
; #pragma unroll
;         for (int d0 = 0; d0 < 4; ++d0) { const float v = o[d0][r] * rli[r];
;             if constexpr (same_t<TOut, float>::v) { Ow[(size_t)orow * OP + d0 * 32 + r32] = v; }
;             else { const float vn = __shfl_xor(v, 1);
;                    if ((r32 & 1) == 0) *(unsigned*)(Ow + (size_t)orow * OP + d0 * 32 + r32) = cvtpk(v, vn); } } }
	v_cvt_pk_bf16_f32 v23, v23, v80
	v_cvt_pk_bf16_f32 v7, v7, v81
	v_mul_f32_e32 v56, v56, v68
	v_mul_f32_e32 v40, v40, v68
	v_mul_f32_e32 v24, v24, v68
	v_mul_f32_e32 v8, v8, v68
	v_mov_b32_dpp v80, v56 quad_perm:[1,0,3,2] row_mask:0xf bank_mask:0xf
	v_mov_b32_dpp v81, v40 quad_perm:[1,0,3,2] row_mask:0xf bank_mask:0xf
	v_cvt_pk_bf16_f32 v56, v56, v80
	v_cvt_pk_bf16_f32 v40, v40, v81
	v_mov_b32_dpp v80, v24 quad_perm:[1,0,3,2] row_mask:0xf bank_mask:0xf
	v_mov_b32_dpp v81, v8 quad_perm:[1,0,3,2] row_mask:0xf bank_mask:0xf
	v_cvt_pk_bf16_f32 v24, v24, v80
	v_cvt_pk_bf16_f32 v8, v8, v81
	v_mul_f32_e32 v57, v57, v69
	v_mul_f32_e32 v41, v41, v69
	v_mul_f32_e32 v25, v25, v69
	v_mul_f32_e32 v9, v9, v69
	v_mov_b32_dpp v80, v57 quad_perm:[1,0,3,2] row_mask:0xf bank_mask:0xf
	v_mov_b32_dpp v81, v41 quad_perm:[1,0,3,2] row_mask:0xf bank_mask:0xf
	v_cvt_pk_bf16_f32 v57, v57, v80
	v_cvt_pk_bf16_f32 v41, v41, v81
	v_mov_b32_dpp v80, v25 quad_perm:[1,0,3,2] row_mask:0xf bank_mask:0xf
	v_mov_b32_dpp v81, v9 quad_perm:[1,0,3,2] row_mask:0xf bank_mask:0xf
	v_cvt_pk_bf16_f32 v25, v25, v80
	v_cvt_pk_bf16_f32 v9, v9, v81
	v_mul_f32_e32 v58, v58, v70
	v_mul_f32_e32 v42, v42, v70
	v_mul_f32_e32 v26, v26, v70
	v_mul_f32_e32 v10, v10, v70
	v_mov_b32_dpp v80, v58 quad_perm:[1,0,3,2] row_mask:0xf bank_mask:0xf
	v_mov_b32_dpp v81, v42 quad_perm:[1,0,3,2] row_mask:0xf bank_mask:0xf
	v_cvt_pk_bf16_f32 v58, v58, v80
	v_cvt_pk_bf16_f32 v42, v42, v81
	v_mov_b32_dpp v80, v26 quad_perm:[1,0,3,2] row_mask:0xf bank_mask:0xf
	v_mov_b32_dpp v81, v10 quad_perm:[1,0,3,2] row_mask:0xf bank_mask:0xf
	v_cvt_pk_bf16_f32 v26, v26, v80
	v_cvt_pk_bf16_f32 v10, v10, v81
	v_mul_f32_e32 v59, v59, v71
	v_mul_f32_e32 v43, v43, v71
	v_mul_f32_e32 v27, v27, v71
	v_mul_f32_e32 v11, v11, v71
	v_mov_b32_dpp v80, v59 quad_perm:[1,0,3,2] row_mask:0xf bank_mask:0xf
	v_mov_b32_dpp v81, v43 quad_perm:[1,0,3,2] row_mask:0xf bank_mask:0xf
	v_cvt_pk_bf16_f32 v59, v59, v80
	v_cvt_pk_bf16_f32 v43, v43, v81
	v_mov_b32_dpp v80, v27 quad_perm:[1,0,3,2] row_mask:0xf bank_mask:0xf
	v_mov_b32_dpp v81, v11 quad_perm:[1,0,3,2] row_mask:0xf bank_mask:0xf
	v_cvt_pk_bf16_f32 v27, v27, v80
	v_cvt_pk_bf16_f32 v11, v11, v81
	v_mul_f32_e32 v60, v60, v64
	v_mul_f32_e32 v44, v44, v64
	v_mul_f32_e32 v28, v28, v64
	v_mul_f32_e32 v12, v12, v64
	v_mov_b32_dpp v80, v60 quad_perm:[1,0,3,2] row_mask:0xf bank_mask:0xf
	v_mov_b32_dpp v81, v44 quad_perm:[1,0,3,2] row_mask:0xf bank_mask:0xf
	v_cvt_pk_bf16_f32 v60, v60, v80
	v_cvt_pk_bf16_f32 v44, v44, v81
	v_mov_b32_dpp v80, v28 quad_perm:[1,0,3,2] row_mask:0xf bank_mask:0xf
	v_mov_b32_dpp v81, v12 quad_perm:[1,0,3,2] row_mask:0xf bank_mask:0xf
	v_cvt_pk_bf16_f32 v28, v28, v80
	v_cvt_pk_bf16_f32 v12, v12, v81
	v_mul_f32_e32 v61, v61, v65
	v_mul_f32_e32 v45, v45, v65
	v_mul_f32_e32 v29, v29, v65
	v_mul_f32_e32 v13, v13, v65
	v_mov_b32_dpp v80, v61 quad_perm:[1,0,3,2] row_mask:0xf bank_mask:0xf
	v_mov_b32_dpp v81, v45 quad_perm:[1,0,3,2] row_mask:0xf bank_mask:0xf
	v_cvt_pk_bf16_f32 v61, v61, v80
	v_cvt_pk_bf16_f32 v45, v45, v81
	v_mov_b32_dpp v80, v29 quad_perm:[1,0,3,2] row_mask:0xf bank_mask:0xf
	v_mov_b32_dpp v81, v13 quad_perm:[1,0,3,2] row_mask:0xf bank_mask:0xf
	v_cvt_pk_bf16_f32 v29, v29, v80
	v_cvt_pk_bf16_f32 v13, v13, v81
	v_mul_f32_e32 v62, v62, v66
	v_mul_f32_e32 v46, v46, v66
	v_mul_f32_e32 v30, v30, v66
	v_mul_f32_e32 v14, v14, v66
	v_mov_b32_dpp v80, v62 quad_perm:[1,0,3,2] row_mask:0xf bank_mask:0xf
	v_mov_b32_dpp v81, v46 quad_perm:[1,0,3,2] row_mask:0xf bank_mask:0xf
	v_cvt_pk_bf16_f32 v62, v62, v80
	v_cvt_pk_bf16_f32 v46, v46, v81
	v_mov_b32_dpp v80, v30 quad_perm:[1,0,3,2] row_mask:0xf bank_mask:0xf
	v_mov_b32_dpp v81, v14 quad_perm:[1,0,3,2] row_mask:0xf bank_mask:0xf
	v_cvt_pk_bf16_f32 v30, v30, v80
	v_cvt_pk_bf16_f32 v14, v14, v81
	v_mul_f32_e32 v63, v63, v67
	v_mul_f32_e32 v47, v47, v67
	v_mul_f32_e32 v31, v31, v67
	v_mul_f32_e32 v15, v15, v67
	v_mov_b32_dpp v80, v63 quad_perm:[1,0,3,2] row_mask:0xf bank_mask:0xf
	v_mov_b32_dpp v81, v47 quad_perm:[1,0,3,2] row_mask:0xf bank_mask:0xf
	v_cvt_pk_bf16_f32 v63, v63, v80
	v_cvt_pk_bf16_f32 v47, v47, v81
	v_mov_b32_dpp v80, v31 quad_perm:[1,0,3,2] row_mask:0xf bank_mask:0xf
	v_mov_b32_dpp v81, v15 quad_perm:[1,0,3,2] row_mask:0xf bank_mask:0xf
	v_cvt_pk_bf16_f32 v31, v31, v80
	v_cvt_pk_bf16_f32 v15, v15, v81
	s_mov_b64 exec, s[40:41]
	ds_write_b32 v82, v48
	ds_write_b32 v82, v32 offset:64
	ds_write_b32 v82, v16 offset:128
	ds_write_b32 v82, v0 offset:192
	ds_write_b32 v82, v49 offset:256
	ds_write_b32 v82, v33 offset:320
	ds_write_b32 v82, v17 offset:384
	ds_write_b32 v82, v1 offset:448
	ds_write_b32 v82, v50 offset:512
	ds_write_b32 v82, v34 offset:576
	ds_write_b32 v82, v18 offset:640
	ds_write_b32 v82, v2 offset:704
	ds_write_b32 v82, v51 offset:768
	ds_write_b32 v82, v35 offset:832
	ds_write_b32 v82, v19 offset:896
	ds_write_b32 v82, v3 offset:960
	ds_write_b32 v82, v52 offset:2048
	ds_write_b32 v82, v36 offset:2112
	ds_write_b32 v82, v20 offset:2176
	ds_write_b32 v82, v4 offset:2240
	ds_write_b32 v82, v53 offset:2304
	ds_write_b32 v82, v37 offset:2368
	ds_write_b32 v82, v21 offset:2432
	ds_write_b32 v82, v5 offset:2496
	ds_write_b32 v82, v54 offset:2560
	ds_write_b32 v82, v38 offset:2624
	ds_write_b32 v82, v22 offset:2688
	ds_write_b32 v82, v6 offset:2752
	ds_write_b32 v82, v55 offset:2816
	ds_write_b32 v82, v39 offset:2880
	ds_write_b32 v82, v23 offset:2944
	ds_write_b32 v82, v7 offset:3008
	ds_write_b32 v82, v56 offset:4096
	ds_write_b32 v82, v40 offset:4160
	ds_write_b32 v82, v24 offset:4224
	ds_write_b32 v82, v8 offset:4288
	ds_write_b32 v82, v57 offset:4352
	ds_write_b32 v82, v41 offset:4416
	ds_write_b32 v82, v25 offset:4480
	ds_write_b32 v82, v9 offset:4544
	ds_write_b32 v82, v58 offset:4608
	ds_write_b32 v82, v42 offset:4672
	ds_write_b32 v82, v26 offset:4736
	ds_write_b32 v82, v10 offset:4800
	ds_write_b32 v82, v59 offset:4864
	ds_write_b32 v82, v43 offset:4928
	ds_write_b32 v82, v27 offset:4992
	ds_write_b32 v82, v11 offset:5056
	ds_write_b32 v82, v60 offset:6144
	ds_write_b32 v82, v44 offset:6208
	ds_write_b32 v82, v28 offset:6272
	ds_write_b32 v82, v12 offset:6336
	ds_write_b32 v82, v61 offset:6400
	ds_write_b32 v82, v45 offset:6464
	ds_write_b32 v82, v29 offset:6528
	ds_write_b32 v82, v13 offset:6592
	ds_write_b32 v82, v62 offset:6656
	ds_write_b32 v82, v46 offset:6720
	ds_write_b32 v82, v30 offset:6784
	ds_write_b32 v82, v14 offset:6848
	ds_write_b32 v82, v63 offset:6912
	ds_write_b32 v82, v47 offset:6976
	ds_write_b32 v82, v31 offset:7040
	ds_write_b32 v82, v15 offset:7104
	s_mov_b64 exec, -1
	v_and_b32_e32 v81, 63, v209
	v_lshrrev_b32_e32 v80, 4, v81
	v_and_b32_e32 v81, 15, v81
	v_lshlrev_b32_e32 v80, 11, v80
	v_lshl_add_u32 v80, v81, 4, v80
	s_waitcnt lgkmcnt(0)
; __device__ __forceinline__ int crow(int r, int hi) { return (r & 3) + 8 * (r >> 2) + 4 * hi; }
; template <class TIn, class TOut>
; __device__ __forceinline__ void causal_swa_block(const BlockRef<TIn, TOut>& cur, const BlockRef<TIn, TOut>& nxt, int skv, int W, char* lds, Seam<TIn>& S, const float* csl) {
;     ...
;     TOut* Ow = cur.O + (size_t)(wid * QBLK) * OP;
; #pragma unroll
;     for (int r = 0; r < 16; ++r) { const int orow = crow(r, hi);
; #pragma unroll
;         for (int d0 = 0; d0 < 4; ++d0) { const float v = o[d0][r] * rli[r];
;             if constexpr (same_t<TOut, float>::v) { Ow[(size_t)orow * OP + d0 * 32 + r32] = v; }
;             else { const float vn = __shfl_xor(v, 1);
;                    if ((r32 & 1) == 0) *(unsigned*)(Ow + (size_t)orow * OP + d0 * 32 + r32) = cvtpk(v, vn); } } }
	ds_read_b128 v[0:3], v83
	ds_read_b128 v[4:7], v83 offset:1024
	ds_read_b128 v[8:11], v83 offset:2048
	ds_read_b128 v[12:15], v83 offset:3072
	ds_read_b128 v[16:19], v83 offset:4096
	ds_read_b128 v[20:23], v83 offset:5120
	ds_read_b128 v[24:27], v83 offset:6144
	ds_read_b128 v[28:31], v83 offset:7168
	s_waitcnt lgkmcnt(7)
	global_store_dwordx4 v80, v[0:3], s[14:15]
	s_add_u32 s14, s14, 0x2000
	s_addc_u32 s15, s15, 0
	s_waitcnt lgkmcnt(6)
	global_store_dwordx4 v80, v[4:7], s[14:15]
	s_add_u32 s14, s14, 0x2000
	s_addc_u32 s15, s15, 0
	s_waitcnt lgkmcnt(5)
	global_store_dwordx4 v80, v[8:11], s[14:15]
	s_add_u32 s14, s14, 0x2000
	s_addc_u32 s15, s15, 0
	s_waitcnt lgkmcnt(4)
	global_store_dwordx4 v80, v[12:15], s[14:15]
	s_add_u32 s14, s14, 0x2000
	s_addc_u32 s15, s15, 0
	s_waitcnt lgkmcnt(3)
	global_store_dwordx4 v80, v[16:19], s[14:15]
	s_add_u32 s14, s14, 0x2000
	s_addc_u32 s15, s15, 0
	s_waitcnt lgkmcnt(2)
	global_store_dwordx4 v80, v[20:23], s[14:15]
	s_add_u32 s14, s14, 0x2000
	s_addc_u32 s15, s15, 0
	s_waitcnt lgkmcnt(1)
	global_store_dwordx4 v80, v[24:27], s[14:15]
	s_add_u32 s14, s14, 0x2000
	s_addc_u32 s15, s15, 0
	s_waitcnt lgkmcnt(0)
	global_store_dwordx4 v80, v[28:31], s[14:15]
	s_branch .LBB0_297
